# comb phase software-pipelined loads; LN(post) parameter loads batched with a single wait per row
# speedup vs baseline: 1.0104x; 1.0033x over previous
.LBB0_706:
	s_andn2_b64 vcc, exec, s[42:43]
	s_cbranch_vccnz .LBB0_777
	v_readlane_b32 s42, v253, 2
	v_readlane_b32 s43, v253, 3
	v_mov_b32_e32 v2, v133
	v_readlane_b32 s38, v253, 20
	v_readlane_b32 s39, v253, 21
	v_ashrrev_i32_e32 v3, 31, v2
	s_nop 0
	v_lshl_add_u64 v[0:1], s[38:39], 0, v[2:3]
	s_mov_b64 s[38:39], 0x500000
	v_cmp_gt_u64_e32 vcc, s[38:39], v[0:1]
	s_and_saveexec_b64 s[44:45], vcc
	s_cbranch_execz .LBB0_714
	s_load_dwordx2 s[38:39], s[42:43], 0xa0
	s_load_dwordx2 s[46:47], s[42:43], 0xf8
	v_readlane_b32 s42, v254, 60
	s_lshl_b32 s2, s42, 12
	v_readlane_b32 s43, v254, 61
	s_waitcnt lgkmcnt(0)
	s_add_u32 s48, s38, s2
	v_readlane_b32 s42, v254, 45
	s_addc_u32 s49, s39, 0
	v_readlane_b32 s38, v254, 53
	v_readlane_b32 s43, v254, 46
	v_readlane_b32 s39, v254, 54
	v_lshlrev_b64 v[34:35], 3, v[0:1]
	v_lshl_add_u64 v[32:33], v[2:3], 4, s[42:43]
	v_lshl_add_u64 v[2:3], s[38:39], 0, v[2:3]
	v_lshlrev_b64 v[36:37], 4, v[2:3]
	s_mov_b64 s[50:51], 0
	v_lshl_add_u64 v[12:13], s[46:47], 0, v[32:33]
	v_lshl_add_u64 v[38:39], v[0:1], 0, s[76:77]
	v_lshl_add_u64 v[40:41], s[46:47], 0, v[36:37]
	s_mov_b64 s[38:39], 0x500000
	v_cmp_gt_u64_e64 s[42:43], s[38:39], v[38:39]
	s_nop 1
	v_and_b32_e32 v234, 0x3f8, v34
	v_lshlrev_b32_e32 v234, 2, v234
	global_load_dwordx4 v[216:219], v234, s[48:49] offset:16
	global_load_dwordx4 v[220:223], v234, s[48:49]
	s_mov_b64 s[38:39], 0x2c600000
	v_lshl_add_u64 v[232:233], v[12:13], 0, s[38:39]
	global_load_dwordx4 v[192:195], v[232:233], off
	s_mov_b64 s[38:39], 0x22600000
	v_lshl_add_u64 v[232:233], v[12:13], 0, s[38:39]
	global_load_dwordx4 v[196:199], v[232:233], off
	s_mov_b64 s[38:39], 0x27600000
	v_lshl_add_u64 v[232:233], v[12:13], 0, s[38:39]
	global_load_dwordx4 v[200:203], v[232:233], off
	s_and_saveexec_b64 s[52:53], s[42:43]
	s_mov_b64 s[38:39], 0x2c600000
	v_lshl_add_u64 v[232:233], v[40:41], 0, s[38:39]
	global_load_dwordx4 v[204:207], v[232:233], off
	s_mov_b64 s[38:39], 0x22600000
	v_lshl_add_u64 v[232:233], v[40:41], 0, s[38:39]
	global_load_dwordx4 v[208:211], v[232:233], off
	s_mov_b64 s[38:39], 0x27600000
	v_lshl_add_u64 v[232:233], v[40:41], 0, s[38:39]
	global_load_dwordx4 v[212:215], v[232:233], off
	s_or_b64 exec, exec, s[52:53]
	s_waitcnt vmcnt(0)
	s_branch .Lcb_top
.LBB0_709:
	s_or_b64 exec, exec, s[52:53]
	v_mov_b64_e32 v[12:13], v[224:225]
	v_mov_b64_e32 v[40:41], v[226:227]
	v_mov_b64_e32 v[38:39], v[228:229]
	s_mov_b64 s[42:43], s[98:99]
	v_readlane_b32 s38, v254, 51
	v_readlane_b32 s39, v254, 52
	s_or_b64 s[50:51], s[100:101], s[50:51]
	s_nop 1
	v_lshl_add_u64 v[34:35], v[34:35], 0, s[38:39]
	s_andn2_b64 exec, exec, s[50:51]
	s_cbranch_execz .LBB0_714
	s_waitcnt vmcnt(1)
.Lcb_top:
	s_mov_b64 s[38:39], 0x27600000
	v_lshl_add_u64 v[42:43], v[12:13], 0, s[38:39]
	v_mov_b64_e32 v[20:21], v[192:193]
	v_mov_b64_e32 v[22:23], v[194:195]
	v_mov_b64_e32 v[24:25], v[196:197]
	v_mov_b64_e32 v[26:27], v[198:199]
	v_mov_b64_e32 v[28:29], v[200:201]
	v_mov_b64_e32 v[30:31], v[202:203]
	v_mov_b64_e32 v[0:1], v[204:205]
	v_mov_b64_e32 v[2:3], v[206:207]
	v_mov_b64_e32 v[8:9], v[208:209]
	v_mov_b64_e32 v[10:11], v[210:211]
	v_mov_b64_e32 v[4:5], v[212:213]
	v_mov_b64_e32 v[6:7], v[214:215]
	v_mov_b64_e32 v[12:13], v[216:217]
	v_mov_b64_e32 v[14:15], v[218:219]
	v_mov_b64_e32 v[16:17], v[220:221]
	v_mov_b64_e32 v[18:19], v[222:223]
	v_readlane_b32 s38, v254, 47
	v_readlane_b32 s39, v254, 48
	s_add_u32 s46, s46, s38
	s_addc_u32 s47, s47, s39
	v_lshl_add_u64 v[230:231], v[38:39], 0, s[76:77]
	s_mov_b64 s[38:39], 0x4fffff
	v_cmp_lt_u64_e64 s[100:101], s[38:39], v[230:231]
	v_lshl_add_u64 v[224:225], s[46:47], 0, v[32:33]
	v_lshl_add_u64 v[226:227], s[46:47], 0, v[36:37]
	v_lshl_add_u64 v[228:229], v[230:231], 0, s[76:77]
	s_mov_b64 s[38:39], 0x500000
	v_cmp_gt_u64_e64 s[98:99], s[38:39], v[228:229]
	v_readlane_b32 s38, v254, 51
	s_nop 1
	v_add_u32_e32 v235, s38, v34
	s_mov_b64 vcc, exec
	s_andn2_b64 exec, exec, s[100:101]
	v_and_b32_e32 v234, 0x3f8, v235
	v_lshlrev_b32_e32 v234, 2, v234
	global_load_dwordx4 v[216:219], v234, s[48:49] offset:16
	global_load_dwordx4 v[220:223], v234, s[48:49]
	s_mov_b64 s[38:39], 0x2c600000
	v_lshl_add_u64 v[232:233], v[224:225], 0, s[38:39]
	global_load_dwordx4 v[192:195], v[232:233], off
	s_mov_b64 s[38:39], 0x22600000
	v_lshl_add_u64 v[232:233], v[224:225], 0, s[38:39]
	global_load_dwordx4 v[196:199], v[232:233], off
	s_mov_b64 s[38:39], 0x27600000
	v_lshl_add_u64 v[232:233], v[224:225], 0, s[38:39]
	global_load_dwordx4 v[200:203], v[232:233], off
	s_and_saveexec_b64 s[52:53], s[98:99]
	s_mov_b64 s[38:39], 0x2c600000
	v_lshl_add_u64 v[232:233], v[226:227], 0, s[38:39]
	global_load_dwordx4 v[204:207], v[232:233], off
	s_mov_b64 s[38:39], 0x22600000
	v_lshl_add_u64 v[232:233], v[226:227], 0, s[38:39]
	global_load_dwordx4 v[208:211], v[232:233], off
	s_mov_b64 s[38:39], 0x27600000
	v_lshl_add_u64 v[232:233], v[226:227], 0, s[38:39]
	global_load_dwordx4 v[212:215], v[232:233], off
	s_or_b64 exec, exec, s[52:53]
	s_mov_b64 exec, vcc
	v_lshlrev_b32_e32 v44, 16, v28
	v_and_b32_e32 v45, 0xffff0000, v28
	v_lshlrev_b32_e32 v46, 16, v20
	v_and_b32_e32 v47, 0xffff0000, v20
	v_pk_add_f32 v[44:45], v[44:45], v[46:47]
	v_lshlrev_b32_e32 v46, 16, v24
	v_and_b32_e32 v47, 0xffff0000, v24
	v_pk_fma_f32 v[44:45], v[16:17], v[46:47], v[44:45]
	s_nop 0
	v_mul_f32_e32 v20, 0x3d372713, v44
	v_mul_f32_e32 v20, v44, v20
	v_fma_f32 v20, v44, v20, v44
	v_mul_f32_e32 v20, 0x3f4c422a, v20
	v_mul_f32_e32 v20, -2.0, v20
	v_mul_f32_e32 v20, 0x3fb8aa3b, v20
	v_exp_f32_e32 v46, v20
	v_mul_f32_e32 v20, 0x3d372713, v45
	v_mul_f32_e32 v20, v45, v20
	v_fma_f32 v20, v45, v20, v45
	v_mul_f32_e32 v20, 0x3f4c422a, v20
	v_mul_f32_e32 v20, -2.0, v20
	v_mul_f32_e32 v20, 0x3fb8aa3b, v20
	v_exp_f32_e32 v47, v20
	s_nop 0
	v_pk_add_f32 v[46:47], v[46:47], 1.0 op_sel_hi:[1,0]
	s_nop 0
	v_div_scale_f32 v20, s[38:39], v47, v47, v45
	v_rcp_f32_e32 v24, v20
	s_nop 0
	v_fma_f32 v28, -v20, v24, 1.0
	v_fmac_f32_e32 v24, v28, v24
	v_div_scale_f32 v28, vcc, v45, v47, v45
	v_mul_f32_e32 v48, v28, v24
	v_fma_f32 v49, -v20, v48, v28
	v_fmac_f32_e32 v48, v49, v24
	v_fma_f32 v20, -v20, v48, v28
	v_div_fmas_f32 v20, v20, v24, v48
	v_div_scale_f32 v24, s[38:39], v46, v46, v44
	v_rcp_f32_e32 v28, v24
	v_div_fixup_f32 v20, v20, v47, v45
	v_fma_f32 v45, -v24, v28, 1.0
	v_fmac_f32_e32 v28, v45, v28
	v_div_scale_f32 v45, vcc, v44, v46, v44
	v_mul_f32_e32 v47, v45, v28
	v_fma_f32 v48, -v24, v47, v45
	v_fmac_f32_e32 v47, v48, v28
	v_fma_f32 v24, -v24, v47, v45
	v_div_fmas_f32 v24, v24, v28, v47
	v_div_fixup_f32 v24, v24, v46, v44
	v_lshlrev_b32_e32 v28, 16, v29
	v_and_b32_e32 v29, 0xffff0000, v29
	v_lshlrev_b32_e32 v44, 16, v21
	v_and_b32_e32 v45, 0xffff0000, v21
	v_cvt_pk_bf16_f32 v20, v24, v20
	v_pk_add_f32 v[28:29], v[28:29], v[44:45]
	v_lshlrev_b32_e32 v24, 16, v25
	v_and_b32_e32 v25, 0xffff0000, v25
	v_pk_fma_f32 v[24:25], v[18:19], v[24:25], v[28:29]
	s_nop 0
	v_mul_f32_e32 v21, 0x3d372713, v24
	v_mul_f32_e32 v21, v24, v21
	v_fma_f32 v21, v24, v21, v24
	v_mul_f32_e32 v21, 0x3f4c422a, v21
	v_mul_f32_e32 v21, -2.0, v21
	v_mul_f32_e32 v21, 0x3fb8aa3b, v21
	v_exp_f32_e32 v28, v21
	v_mul_f32_e32 v21, 0x3d372713, v25
	v_mul_f32_e32 v21, v25, v21
	v_fma_f32 v21, v25, v21, v25
	v_mul_f32_e32 v21, 0x3f4c422a, v21
	v_mul_f32_e32 v21, -2.0, v21
	v_mul_f32_e32 v21, 0x3fb8aa3b, v21
	v_exp_f32_e32 v29, v21
	s_nop 0
	v_pk_add_f32 v[28:29], v[28:29], 1.0 op_sel_hi:[1,0]
	s_nop 0
	v_div_scale_f32 v21, s[38:39], v29, v29, v25
	v_rcp_f32_e32 v44, v21
	s_nop 0
	v_fma_f32 v45, -v21, v44, 1.0
	v_fmac_f32_e32 v44, v45, v44
	v_div_scale_f32 v45, vcc, v25, v29, v25
	v_mul_f32_e32 v46, v45, v44
	v_fma_f32 v47, -v21, v46, v45
	v_fmac_f32_e32 v46, v47, v44
	v_fma_f32 v21, -v21, v46, v45
	v_div_fmas_f32 v21, v21, v44, v46
	v_div_fixup_f32 v21, v21, v29, v25
	v_div_scale_f32 v25, s[38:39], v28, v28, v24
	v_rcp_f32_e32 v29, v25
	s_nop 0
	v_fma_f32 v44, -v25, v29, 1.0
	v_fmac_f32_e32 v29, v44, v29
	v_div_scale_f32 v44, vcc, v24, v28, v24
	v_mul_f32_e32 v45, v44, v29
	v_fma_f32 v46, -v25, v45, v44
	v_fmac_f32_e32 v45, v46, v29
	v_fma_f32 v25, -v25, v45, v44
	v_div_fmas_f32 v25, v25, v29, v45
	v_div_fixup_f32 v24, v25, v28, v24
	v_cvt_pk_bf16_f32 v21, v24, v21
	v_lshlrev_b32_e32 v24, 16, v30
	v_and_b32_e32 v25, 0xffff0000, v30
	v_lshlrev_b32_e32 v28, 16, v22
	v_and_b32_e32 v29, 0xffff0000, v22
	v_pk_add_f32 v[24:25], v[24:25], v[28:29]
	v_lshlrev_b32_e32 v28, 16, v26
	v_and_b32_e32 v29, 0xffff0000, v26
	v_pk_fma_f32 v[24:25], v[12:13], v[28:29], v[24:25]
	s_nop 0
	v_mul_f32_e32 v22, 0x3d372713, v24
	v_mul_f32_e32 v22, v24, v22
	v_fma_f32 v22, v24, v22, v24
	v_mul_f32_e32 v22, 0x3f4c422a, v22
	v_mul_f32_e32 v22, -2.0, v22
	v_mul_f32_e32 v22, 0x3fb8aa3b, v22
	v_exp_f32_e32 v28, v22
	v_mul_f32_e32 v22, 0x3d372713, v25
	v_mul_f32_e32 v22, v25, v22
	v_fma_f32 v22, v25, v22, v25
	v_mul_f32_e32 v22, 0x3f4c422a, v22
	v_mul_f32_e32 v22, -2.0, v22
	v_mul_f32_e32 v22, 0x3fb8aa3b, v22
	v_exp_f32_e32 v29, v22
	s_nop 0
	v_pk_add_f32 v[28:29], v[28:29], 1.0 op_sel_hi:[1,0]
	s_nop 0
	v_div_scale_f32 v22, s[38:39], v29, v29, v25
	v_rcp_f32_e32 v26, v22
	s_nop 0
	v_fma_f32 v30, -v22, v26, 1.0
	v_fmac_f32_e32 v26, v30, v26
	v_div_scale_f32 v30, vcc, v25, v29, v25
	v_mul_f32_e32 v44, v30, v26
	v_fma_f32 v45, -v22, v44, v30
	v_fmac_f32_e32 v44, v45, v26
	v_fma_f32 v22, -v22, v44, v30
	v_div_fmas_f32 v22, v22, v26, v44
	v_div_fixup_f32 v22, v22, v29, v25
	v_div_scale_f32 v25, s[38:39], v28, v28, v24
	v_rcp_f32_e32 v26, v25
	s_nop 0
	v_fma_f32 v29, -v25, v26, 1.0
	v_fmac_f32_e32 v26, v29, v26
	v_div_scale_f32 v29, vcc, v24, v28, v24
	v_mul_f32_e32 v30, v29, v26
	v_fma_f32 v44, -v25, v30, v29
	v_fmac_f32_e32 v30, v44, v26
	v_fma_f32 v25, -v25, v30, v29
	v_div_fmas_f32 v25, v25, v26, v30
	v_div_fixup_f32 v24, v25, v28, v24
	v_cvt_pk_bf16_f32 v22, v24, v22
	v_lshlrev_b32_e32 v24, 16, v31
	v_and_b32_e32 v25, 0xffff0000, v31
	v_lshlrev_b32_e32 v28, 16, v23
	v_and_b32_e32 v29, 0xffff0000, v23
	v_pk_add_f32 v[24:25], v[24:25], v[28:29]
	v_lshlrev_b32_e32 v26, 16, v27
	v_and_b32_e32 v27, 0xffff0000, v27
	v_pk_fma_f32 v[24:25], v[14:15], v[26:27], v[24:25]
	s_nop 0
	v_mul_f32_e32 v23, 0x3d372713, v24
	v_mul_f32_e32 v23, v24, v23
	v_fma_f32 v23, v24, v23, v24
	v_mul_f32_e32 v23, 0x3f4c422a, v23
	v_mul_f32_e32 v23, -2.0, v23
	v_mul_f32_e32 v23, 0x3fb8aa3b, v23
	v_exp_f32_e32 v26, v23
	v_mul_f32_e32 v23, 0x3d372713, v25
	v_mul_f32_e32 v23, v25, v23
	v_fma_f32 v23, v25, v23, v25
	v_mul_f32_e32 v23, 0x3f4c422a, v23
	v_mul_f32_e32 v23, -2.0, v23
	v_mul_f32_e32 v23, 0x3fb8aa3b, v23
	v_exp_f32_e32 v27, v23
	s_nop 0
	v_pk_add_f32 v[26:27], v[26:27], 1.0 op_sel_hi:[1,0]
	s_nop 0
	v_div_scale_f32 v23, s[38:39], v27, v27, v25
	v_rcp_f32_e32 v28, v23
	s_nop 0
	v_fma_f32 v29, -v23, v28, 1.0
	v_fmac_f32_e32 v28, v29, v28
	v_div_scale_f32 v29, vcc, v25, v27, v25
	v_mul_f32_e32 v30, v29, v28
	v_fma_f32 v31, -v23, v30, v29
	v_fmac_f32_e32 v30, v31, v28
	v_fma_f32 v23, -v23, v30, v29
	v_div_fmas_f32 v23, v23, v28, v30
	v_div_fixup_f32 v23, v23, v27, v25
	v_div_scale_f32 v25, s[38:39], v26, v26, v24
	v_rcp_f32_e32 v27, v25
	s_nop 0
	v_fma_f32 v28, -v25, v27, 1.0
	v_fmac_f32_e32 v27, v28, v27
	v_div_scale_f32 v28, vcc, v24, v26, v24
	v_mul_f32_e32 v29, v28, v27
	v_fma_f32 v30, -v25, v29, v28
	v_fmac_f32_e32 v29, v30, v27
	v_fma_f32 v25, -v25, v29, v28
	v_div_fmas_f32 v25, v25, v27, v29
	v_div_fixup_f32 v24, v25, v26, v24
	v_cvt_pk_bf16_f32 v23, v24, v23
	global_store_dwordx4 v[42:43], v[20:23], off
	s_and_saveexec_b64 s[52:53], s[42:43]
	s_cbranch_execz .LBB0_709
	v_lshlrev_b32_e32 v20, 16, v4
	v_and_b32_e32 v21, 0xffff0000, v4
	v_lshlrev_b32_e32 v22, 16, v0
	v_and_b32_e32 v23, 0xffff0000, v0
	v_pk_add_f32 v[20:21], v[22:23], v[20:21]
	v_lshlrev_b32_e32 v22, 16, v8
	v_and_b32_e32 v23, 0xffff0000, v8
	v_pk_fma_f32 v[16:17], v[16:17], v[22:23], v[20:21]
	s_nop 0
	v_mul_f32_e32 v0, 0x3d372713, v16
	v_mul_f32_e32 v0, v16, v0
	v_fma_f32 v0, v16, v0, v16
	v_mul_f32_e32 v0, 0x3f4c422a, v0
	v_mul_f32_e32 v0, -2.0, v0
	v_mul_f32_e32 v0, 0x3fb8aa3b, v0
	v_exp_f32_e32 v20, v0
	v_mul_f32_e32 v0, 0x3d372713, v17
	v_mul_f32_e32 v0, v17, v0
	v_fma_f32 v0, v17, v0, v17
	v_mul_f32_e32 v0, 0x3f4c422a, v0
	v_mul_f32_e32 v0, -2.0, v0
	v_mul_f32_e32 v0, 0x3fb8aa3b, v0
	v_exp_f32_e32 v21, v0
	s_nop 0
	v_pk_add_f32 v[20:21], v[20:21], 1.0 op_sel_hi:[1,0]
	s_nop 0
	v_div_scale_f32 v0, s[38:39], v21, v21, v17
	v_rcp_f32_e32 v4, v0
	s_nop 0
	v_fma_f32 v8, -v0, v4, 1.0
	v_fmac_f32_e32 v4, v8, v4
	v_div_scale_f32 v8, vcc, v17, v21, v17
	v_mul_f32_e32 v22, v8, v4
	v_fma_f32 v23, -v0, v22, v8
	v_fmac_f32_e32 v22, v23, v4
	v_fma_f32 v0, -v0, v22, v8
	v_div_fmas_f32 v0, v0, v4, v22
	v_div_scale_f32 v4, s[38:39], v20, v20, v16
	v_rcp_f32_e32 v8, v4
	v_div_fixup_f32 v0, v0, v21, v17
	v_fma_f32 v17, -v4, v8, 1.0
	v_fmac_f32_e32 v8, v17, v8
	v_div_scale_f32 v17, vcc, v16, v20, v16
	v_mul_f32_e32 v21, v17, v8
	v_fma_f32 v22, -v4, v21, v17
	v_fmac_f32_e32 v21, v22, v8
	v_fma_f32 v4, -v4, v21, v17
	v_div_fmas_f32 v4, v4, v8, v21
	v_div_fixup_f32 v4, v4, v20, v16
	v_cvt_pk_bf16_f32 v0, v4, v0
	v_lshlrev_b32_e32 v4, 16, v5
	v_and_b32_e32 v5, 0xffff0000, v5
	v_lshlrev_b32_e32 v16, 16, v1
	v_and_b32_e32 v17, 0xffff0000, v1
	v_pk_add_f32 v[4:5], v[16:17], v[4:5]
	v_lshlrev_b32_e32 v8, 16, v9
	v_and_b32_e32 v9, 0xffff0000, v9
	v_pk_fma_f32 v[4:5], v[18:19], v[8:9], v[4:5]
	s_nop 0
	v_mul_f32_e32 v1, 0x3d372713, v4
	v_mul_f32_e32 v1, v4, v1
	v_fma_f32 v1, v4, v1, v4
	v_mul_f32_e32 v1, 0x3f4c422a, v1
	v_mul_f32_e32 v1, -2.0, v1
	v_mul_f32_e32 v1, 0x3fb8aa3b, v1
	v_exp_f32_e32 v8, v1
	v_mul_f32_e32 v1, 0x3d372713, v5
	v_mul_f32_e32 v1, v5, v1
	v_fma_f32 v1, v5, v1, v5
	v_mul_f32_e32 v1, 0x3f4c422a, v1
	v_mul_f32_e32 v1, -2.0, v1
	v_mul_f32_e32 v1, 0x3fb8aa3b, v1
	v_exp_f32_e32 v9, v1
	s_nop 0
	v_pk_add_f32 v[8:9], v[8:9], 1.0 op_sel_hi:[1,0]
	s_nop 0
	v_div_scale_f32 v1, s[38:39], v9, v9, v5
	v_rcp_f32_e32 v16, v1
	s_nop 0
	v_fma_f32 v17, -v1, v16, 1.0
	v_fmac_f32_e32 v16, v17, v16
	v_div_scale_f32 v17, vcc, v5, v9, v5
	v_mul_f32_e32 v18, v17, v16
	v_fma_f32 v19, -v1, v18, v17
	v_fmac_f32_e32 v18, v19, v16
	v_fma_f32 v1, -v1, v18, v17
	v_div_fmas_f32 v1, v1, v16, v18
	v_div_fixup_f32 v1, v1, v9, v5
	v_div_scale_f32 v5, s[38:39], v8, v8, v4
	v_rcp_f32_e32 v9, v5
	s_nop 0
	v_fma_f32 v16, -v5, v9, 1.0
	v_fmac_f32_e32 v9, v16, v9
	v_div_scale_f32 v16, vcc, v4, v8, v4
	v_mul_f32_e32 v17, v16, v9
	v_fma_f32 v18, -v5, v17, v16
	v_fmac_f32_e32 v17, v18, v9
	v_fma_f32 v5, -v5, v17, v16
	v_div_fmas_f32 v5, v5, v9, v17
	v_div_fixup_f32 v4, v5, v8, v4
	v_cvt_pk_bf16_f32 v1, v4, v1
	v_lshlrev_b32_e32 v4, 16, v6
	v_and_b32_e32 v5, 0xffff0000, v6
	v_lshlrev_b32_e32 v8, 16, v2
	v_and_b32_e32 v9, 0xffff0000, v2
	v_pk_add_f32 v[4:5], v[8:9], v[4:5]
	v_lshlrev_b32_e32 v8, 16, v10
	v_and_b32_e32 v9, 0xffff0000, v10
	v_pk_fma_f32 v[4:5], v[12:13], v[8:9], v[4:5]
	s_nop 0
	v_mul_f32_e32 v2, 0x3d372713, v4
	v_mul_f32_e32 v2, v4, v2
	v_fma_f32 v2, v4, v2, v4
	v_mul_f32_e32 v2, 0x3f4c422a, v2
	v_mul_f32_e32 v2, -2.0, v2
	v_mul_f32_e32 v2, 0x3fb8aa3b, v2
	v_exp_f32_e32 v8, v2
	v_mul_f32_e32 v2, 0x3d372713, v5
	v_mul_f32_e32 v2, v5, v2
	v_fma_f32 v2, v5, v2, v5
	v_mul_f32_e32 v2, 0x3f4c422a, v2
	v_mul_f32_e32 v2, -2.0, v2
	v_mul_f32_e32 v2, 0x3fb8aa3b, v2
	v_exp_f32_e32 v9, v2
	s_nop 0
	v_pk_add_f32 v[8:9], v[8:9], 1.0 op_sel_hi:[1,0]
	s_nop 0
	v_div_scale_f32 v2, s[38:39], v9, v9, v5
	v_rcp_f32_e32 v6, v2
	s_nop 0
	v_fma_f32 v10, -v2, v6, 1.0
	v_fmac_f32_e32 v6, v10, v6
	v_div_scale_f32 v10, vcc, v5, v9, v5
	v_mul_f32_e32 v12, v10, v6
	v_fma_f32 v13, -v2, v12, v10
	v_fmac_f32_e32 v12, v13, v6
	v_fma_f32 v2, -v2, v12, v10
	v_div_fmas_f32 v2, v2, v6, v12
	v_div_fixup_f32 v2, v2, v9, v5
	v_div_scale_f32 v5, s[38:39], v8, v8, v4
	v_rcp_f32_e32 v6, v5
	s_nop 0
	v_fma_f32 v9, -v5, v6, 1.0
	v_fmac_f32_e32 v6, v9, v6
	v_div_scale_f32 v9, vcc, v4, v8, v4
	v_mul_f32_e32 v10, v9, v6
	v_fma_f32 v12, -v5, v10, v9
	v_fmac_f32_e32 v10, v12, v6
	v_fma_f32 v5, -v5, v10, v9
	v_div_fmas_f32 v5, v5, v6, v10
	v_div_fixup_f32 v4, v5, v8, v4
	v_cvt_pk_bf16_f32 v2, v4, v2
	v_lshlrev_b32_e32 v4, 16, v7
	v_and_b32_e32 v5, 0xffff0000, v7
	v_lshlrev_b32_e32 v6, 16, v3
	v_and_b32_e32 v7, 0xffff0000, v3
	v_pk_add_f32 v[4:5], v[6:7], v[4:5]
	v_lshlrev_b32_e32 v6, 16, v11
	v_and_b32_e32 v7, 0xffff0000, v11
	v_pk_fma_f32 v[4:5], v[14:15], v[6:7], v[4:5]
	s_nop 0
	v_mul_f32_e32 v3, 0x3d372713, v4
	v_mul_f32_e32 v3, v4, v3
	v_fma_f32 v3, v4, v3, v4
	v_mul_f32_e32 v3, 0x3f4c422a, v3
	v_mul_f32_e32 v3, -2.0, v3
	v_mul_f32_e32 v3, 0x3fb8aa3b, v3
	v_exp_f32_e32 v6, v3
	v_mul_f32_e32 v3, 0x3d372713, v5
	v_mul_f32_e32 v3, v5, v3
	v_fma_f32 v3, v5, v3, v5
	v_mul_f32_e32 v3, 0x3f4c422a, v3
	v_mul_f32_e32 v3, -2.0, v3
	v_mul_f32_e32 v3, 0x3fb8aa3b, v3
	v_exp_f32_e32 v7, v3
	s_nop 0
	v_pk_add_f32 v[6:7], v[6:7], 1.0 op_sel_hi:[1,0]
	s_nop 0
	v_div_scale_f32 v3, s[38:39], v7, v7, v5
	v_rcp_f32_e32 v8, v3
	s_nop 0
	v_fma_f32 v9, -v3, v8, 1.0
	v_fmac_f32_e32 v8, v9, v8
	v_div_scale_f32 v9, vcc, v5, v7, v5
	v_mul_f32_e32 v10, v9, v8
	v_fma_f32 v11, -v3, v10, v9
	v_fmac_f32_e32 v10, v11, v8
	v_fma_f32 v3, -v3, v10, v9
	v_div_fmas_f32 v3, v3, v8, v10
	v_div_fixup_f32 v3, v3, v7, v5
	v_div_scale_f32 v5, s[38:39], v6, v6, v4
	v_rcp_f32_e32 v7, v5
	s_nop 0
	v_fma_f32 v8, -v5, v7, 1.0
	v_fmac_f32_e32 v7, v8, v7
	v_div_scale_f32 v8, vcc, v4, v6, v4
	v_mul_f32_e32 v9, v8, v7
	v_fma_f32 v10, -v5, v9, v8
	v_fmac_f32_e32 v9, v10, v7
	v_fma_f32 v5, -v5, v9, v8
	v_div_fmas_f32 v5, v5, v7, v9
	v_div_fixup_f32 v4, v5, v6, v4
	v_cvt_pk_bf16_f32 v3, v4, v3
	v_add_co_u32_e32 v4, vcc, 0x27600000, v40
	s_nop 1
	v_addc_co_u32_e32 v5, vcc, 0, v41, vcc
	global_store_dwordx4 v[4:5], v[0:3], off
	s_branch .LBB0_709

.LBB0_1132:
	s_or_b64 exec, exec, s[44:45]
	v_add_u32_e32 v224, 0xffffe000, v0
	v_lshrrev_b32_e32 v224, 12, v224
	v_add_u32_e32 v224, 1, v224
	v_cmp_lt_i32_e64 s[98:99], s22, v0
	v_mov_b64_e32 v[226:227], s[50:51]
	v_lshlrev_b32_e32 v230, 2, v4
	v_mov_b32_e32 v231, 0
	v_cndmask_b32_e64 v224, 0, v224, s[98:99]
	v_mad_u64_u32 v[226:227], s[100:101], v224, s23, v[226:227]
	s_mov_b64 s[98:99], 0x1000
	global_load_dwordx4 v[134:137], v[6:7], off
	global_load_dwordx4 v[150:153], v[8:9], off
	global_load_dwordx4 v[138:141], v[6:7], off offset:1024
	global_load_dwordx4 v[154:157], v[8:9], off offset:1024
	global_load_dwordx4 v[142:145], v[6:7], off offset:2048
	global_load_dwordx4 v[158:161], v[8:9], off offset:2048
	global_load_dwordx4 v[146:149], v[6:7], off offset:3072
	global_load_dwordx4 v[162:165], v[8:9], off offset:3072
	s_and_b64 vcc, exec, s[48:49]
	s_cbranch_vccz .Lln1_nomod
	v_lshl_add_u64 v[228:229], v[226:227], 0, v[230:231]
	v_lshl_add_u64 v[232:233], v[228:229], 0, s[98:99]
	global_load_dwordx4 v[192:195], v[228:229], off
	global_load_dwordx4 v[208:211], v[232:233], off
	global_load_dwordx4 v[196:199], v[228:229], off offset:1024
	global_load_dwordx4 v[212:215], v[232:233], off offset:1024
	global_load_dwordx4 v[200:203], v[228:229], off offset:2048
	global_load_dwordx4 v[216:219], v[232:233], off offset:2048
	global_load_dwordx4 v[204:207], v[228:229], off offset:3072
	global_load_dwordx4 v[220:223], v[232:233], off offset:3072
.Lln1_nomod:
	v_lshlrev_b32_e32 v44, 16, v36
	v_and_b32_e32 v45, 0xffff0000, v36
	v_add_f32_e32 v1, 0, v44
	v_lshlrev_b32_e32 v46, 16, v37
	v_add_f32_e32 v1, v1, v45
	v_and_b32_e32 v47, 0xffff0000, v37
	v_add_f32_e32 v1, v1, v46
	v_lshlrev_b32_e32 v36, 16, v34
	v_add_f32_e32 v1, v1, v47
	v_and_b32_e32 v37, 0xffff0000, v34
	v_add_f32_e32 v1, v1, v36
	v_lshlrev_b32_e32 v34, 16, v35
	v_add_f32_e32 v1, v1, v37
	v_and_b32_e32 v35, 0xffff0000, v35
	v_add_f32_e32 v1, v1, v34
	v_lshlrev_b32_e32 v38, 16, v32
	v_add_f32_e32 v1, v1, v35
	v_and_b32_e32 v39, 0xffff0000, v32
	v_add_f32_e32 v1, v1, v38
	v_lshlrev_b32_e32 v32, 16, v33
	v_add_f32_e32 v1, v1, v39
	v_and_b32_e32 v33, 0xffff0000, v33
	v_add_f32_e32 v1, v1, v32
	v_lshlrev_b32_e32 v58, 16, v2
	v_add_f32_e32 v1, v1, v33
	v_and_b32_e32 v59, 0xffff0000, v2
	v_add_f32_e32 v1, v1, v58
	v_lshlrev_b32_e32 v2, 16, v3
	v_add_f32_e32 v1, v1, v59
	v_and_b32_e32 v3, 0xffff0000, v3
	v_add_f32_e32 v1, v1, v2
	v_add_f32_e32 v1, v1, v3
	v_cmp_lt_i32_e32 vcc, s22, v0
	s_mov_b64 s[44:45], -1
	v_lshlrev_b32_e32 v128, 2, v4
	s_waitcnt lgkmcnt(0)
	s_nop 1
	v_add_f32_dpp v1, v1, v1 quad_perm:[1,0,3,2] row_mask:0xf bank_mask:0xf
	s_nop 1
	v_add_f32_dpp v1, v1, v1 quad_perm:[2,3,0,1] row_mask:0xf bank_mask:0xf
	s_nop 1
	v_add_f32_dpp v1, v1, v1 row_half_mirror row_mask:0xf bank_mask:0xf
	s_nop 1
	v_add_f32_dpp v1, v1, v1 row_mirror row_mask:0xf bank_mask:0xf
	s_nop 1
	v_mov_b32_e32 v19, v1
	v_mov_b32_e32 v250, v1
	s_nop 1
	v_permlane16_swap_b32 v19, v250
	s_nop 1
	v_add_f32_e32 v1, v19, v250
	v_mov_b32_e32 v19, v1
	v_mov_b32_e32 v250, v1
	s_nop 1
	v_permlane32_swap_b32 v19, v250
	s_nop 1
	v_add_f32_e32 v1, v19, v250
	v_mul_f32_e32 v62, 0x3a800000, v1
	v_add_u32_e32 v1, 0xffffe000, v0
	v_lshrrev_b32_e32 v1, 12, v1
	v_add_u32_e32 v1, 1, v1
	v_pk_add_f32 v[40:41], v[38:39], v[62:63] op_sel_hi:[1,0] neg_lo:[0,1] neg_hi:[0,1]
	v_pk_add_f32 v[38:39], v[2:3], v[62:63] op_sel_hi:[1,0] neg_lo:[0,1] neg_hi:[0,1]
	v_cndmask_b32_e32 v2, 0, v1, vcc
	v_mov_b64_e32 v[0:1], s[50:51]
	v_pk_add_f32 v[48:49], v[36:37], v[62:63] op_sel_hi:[1,0] neg_lo:[0,1] neg_hi:[0,1]
	v_pk_add_f32 v[50:51], v[34:35], v[62:63] op_sel_hi:[1,0] neg_lo:[0,1] neg_hi:[0,1]
	v_pk_add_f32 v[36:37], v[58:59], v[62:63] op_sel_hi:[1,0] neg_lo:[0,1] neg_hi:[0,1]
	v_mad_u64_u32 v[34:35], s[2:3], v2, s23, v[0:1]
	v_pk_add_f32 v[44:45], v[44:45], v[62:63] op_sel_hi:[1,0] neg_lo:[0,1] neg_hi:[0,1]
	v_pk_add_f32 v[42:43], v[32:33], v[62:63] op_sel_hi:[1,0] neg_lo:[0,1] neg_hi:[0,1]
	v_pk_add_f32 v[76:77], v[46:47], v[62:63] op_sel_hi:[1,0] neg_lo:[0,1] neg_hi:[0,1]
	v_pk_mul_f32 v[62:63], v[44:45], v[44:45]
	v_pk_mul_f32 v[46:47], v[76:77], v[76:77]
	v_add_f32_e32 v19, v62, v63
	v_add_f32_e32 v19, v46, v19
	v_pk_mul_f32 v[64:65], v[48:49], v[48:49]
	v_add_f32_e32 v19, v47, v19
	v_add_f32_e32 v19, v64, v19
	v_pk_mul_f32 v[66:67], v[50:51], v[50:51]
	v_add_f32_e32 v19, v65, v19
	v_add_f32_e32 v19, v66, v19
	v_pk_mul_f32 v[68:69], v[40:41], v[40:41]
	v_add_f32_e32 v19, v67, v19
	v_add_f32_e32 v19, v68, v19
	v_pk_mul_f32 v[70:71], v[42:43], v[42:43]
	v_add_f32_e32 v19, v69, v19
	v_add_f32_e32 v19, v70, v19
	v_pk_mul_f32 v[72:73], v[36:37], v[36:37]
	v_add_f32_e32 v19, v71, v19
	v_add_f32_e32 v19, v72, v19
	v_pk_mul_f32 v[74:75], v[38:39], v[38:39]
	v_add_f32_e32 v19, v73, v19
	v_add_f32_e32 v19, v74, v19
	v_add_f32_e32 v19, v75, v19
	s_mov_b64 s[2:3], 0x1000
	v_lshl_add_u64 v[32:33], v[34:35], 0, s[2:3]
	s_waitcnt lgkmcnt(0)
	s_nop 1
	v_add_f32_dpp v19, v19, v19 quad_perm:[1,0,3,2] row_mask:0xf bank_mask:0xf
	s_nop 1
	v_add_f32_dpp v19, v19, v19 quad_perm:[2,3,0,1] row_mask:0xf bank_mask:0xf
	s_nop 1
	v_add_f32_dpp v19, v19, v19 row_half_mirror row_mask:0xf bank_mask:0xf
	s_nop 1
	v_add_f32_dpp v19, v19, v19 row_mirror row_mask:0xf bank_mask:0xf
	s_nop 1
	v_mov_b32_e32 v21, v19
	v_mov_b32_e32 v250, v19
	s_nop 1
	v_permlane16_swap_b32 v21, v250
	s_nop 1
	v_add_f32_e32 v19, v21, v250
	v_mov_b32_e32 v21, v19
	v_mov_b32_e32 v250, v19
	s_nop 1
	v_permlane32_swap_b32 v21, v250
	s_nop 1
	v_add_f32_e32 v19, v21, v250
	v_fmamk_f32 v19, v19, 0x3a800000, v182
	v_cmp_gt_f32_e32 vcc, s13, v19
	v_mul_f32_e32 v21, 0x4b800000, v19
	s_nop 0
	v_cndmask_b32_e32 v19, v19, v21, vcc
	v_rsq_f32_e32 v19, v19
	s_nop 0
	v_mul_f32_e32 v21, 0x45800000, v19
	v_cndmask_b32_e32 v46, v19, v21, vcc
	s_waitcnt vmcnt(0)
	v_lshl_add_u64 v[74:75], v[14:15], 0, v[10:11]
	s_and_b64 vcc, exec, s[48:49]
	s_cbranch_vccz .Lln1_last
	v_add_co_u32_e32 v0, vcc, s25, v74
	s_nop 1
	v_addc_co_u32_e32 v1, vcc, 0, v75, vcc
	v_add_co_u32_e32 v2, vcc, 0x1d600000, v74
	s_nop 1
	v_addc_co_u32_e32 v3, vcc, 0, v75, vcc
	v_pk_mul_f32 v[58:59], v[44:45], v[46:47] op_sel_hi:[1,0]
	v_pk_mul_f32 v[60:61], v[76:77], v[46:47] op_sel_hi:[1,0]
	v_pk_add_f32 v[62:63], v[208:209], 1.0 op_sel_hi:[1,0]
	v_pk_add_f32 v[64:65], v[210:211], 1.0 op_sel_hi:[1,0]
	v_pk_fma_f32 v[58:59], v[134:135], v[58:59], v[150:151]
	v_pk_fma_f32 v[60:61], v[136:137], v[60:61], v[152:153]
	s_nop 0
	v_pk_fma_f32 v[66:67], v[58:59], v[62:63], v[192:193]
	v_pk_fma_f32 v[68:69], v[60:61], v[64:65], v[194:195]
	v_cvt_pk_bf16_f32 v70, v58, v59
	v_cvt_pk_bf16_f32 v71, v60, v61
	v_cvt_pk_bf16_f32 v72, v66, v67
	v_cvt_pk_bf16_f32 v73, v68, v69
	global_store_dwordx2 v[0:1], v[70:71], off
	global_store_dwordx2 v[2:3], v[72:73], off
	v_pk_mul_f32 v[58:59], v[48:49], v[46:47] op_sel_hi:[1,0]
	v_pk_mul_f32 v[60:61], v[50:51], v[46:47] op_sel_hi:[1,0]
	v_pk_add_f32 v[62:63], v[212:213], 1.0 op_sel_hi:[1,0]
	v_pk_add_f32 v[64:65], v[214:215], 1.0 op_sel_hi:[1,0]
	v_pk_fma_f32 v[58:59], v[138:139], v[58:59], v[154:155]
	v_pk_fma_f32 v[60:61], v[140:141], v[60:61], v[156:157]
	s_nop 0
	v_pk_fma_f32 v[66:67], v[58:59], v[62:63], v[196:197]
	v_pk_fma_f32 v[68:69], v[60:61], v[64:65], v[198:199]
	v_cvt_pk_bf16_f32 v32, v58, v59
	v_cvt_pk_bf16_f32 v33, v60, v61
	v_cvt_pk_bf16_f32 v34, v66, v67
	v_cvt_pk_bf16_f32 v35, v68, v69
	global_store_dwordx2 v[0:1], v[32:33], off offset:512
	global_store_dwordx2 v[2:3], v[34:35], off offset:512
	v_pk_mul_f32 v[58:59], v[40:41], v[46:47] op_sel_hi:[1,0]
	v_pk_mul_f32 v[60:61], v[42:43], v[46:47] op_sel_hi:[1,0]
	v_pk_add_f32 v[62:63], v[216:217], 1.0 op_sel_hi:[1,0]
	v_pk_add_f32 v[64:65], v[218:219], 1.0 op_sel_hi:[1,0]
	v_pk_fma_f32 v[58:59], v[142:143], v[58:59], v[158:159]
	v_pk_fma_f32 v[60:61], v[144:145], v[60:61], v[160:161]
	s_nop 0
	v_pk_fma_f32 v[66:67], v[58:59], v[62:63], v[200:201]
	v_pk_fma_f32 v[68:69], v[60:61], v[64:65], v[202:203]
	v_cvt_pk_bf16_f32 v70, v58, v59
	v_cvt_pk_bf16_f32 v71, v60, v61
	v_cvt_pk_bf16_f32 v72, v66, v67
	v_cvt_pk_bf16_f32 v73, v68, v69
	global_store_dwordx2 v[0:1], v[70:71], off offset:1024
	global_store_dwordx2 v[2:3], v[72:73], off offset:1024
	v_pk_mul_f32 v[58:59], v[36:37], v[46:47] op_sel_hi:[1,0]
	v_pk_mul_f32 v[60:61], v[38:39], v[46:47] op_sel_hi:[1,0]
	v_pk_add_f32 v[62:63], v[220:221], 1.0 op_sel_hi:[1,0]
	v_pk_add_f32 v[64:65], v[222:223], 1.0 op_sel_hi:[1,0]
	v_pk_fma_f32 v[58:59], v[146:147], v[58:59], v[162:163]
	v_pk_fma_f32 v[60:61], v[148:149], v[60:61], v[164:165]
	s_nop 0
	v_pk_fma_f32 v[66:67], v[58:59], v[62:63], v[204:205]
	v_pk_fma_f32 v[68:69], v[60:61], v[64:65], v[206:207]
	v_cvt_pk_bf16_f32 v32, v58, v59
	v_cvt_pk_bf16_f32 v33, v60, v61
	v_cvt_pk_bf16_f32 v34, v66, v67
	v_cvt_pk_bf16_f32 v35, v68, v69
	global_store_dwordx2 v[0:1], v[32:33], off offset:1536
	global_store_dwordx2 v[2:3], v[34:35], off offset:1536
	s_branch .LBB0_1129
.Lln1_last:
	v_pk_mul_f32 v[58:59], v[44:45], v[46:47] op_sel_hi:[1,0]
	v_pk_mul_f32 v[60:61], v[76:77], v[46:47] op_sel_hi:[1,0]
	v_pk_fma_f32 v[58:59], v[134:135], v[58:59], v[150:151]
	v_pk_fma_f32 v[60:61], v[136:137], v[60:61], v[152:153]
	s_nop 0
	global_store_dwordx4 v[16:17], v[58:61], off offset:-2048
	v_pk_mul_f32 v[62:63], v[48:49], v[46:47] op_sel_hi:[1,0]
	v_pk_mul_f32 v[64:65], v[50:51], v[46:47] op_sel_hi:[1,0]
	v_pk_fma_f32 v[62:63], v[138:139], v[62:63], v[154:155]
	v_pk_fma_f32 v[64:65], v[140:141], v[64:65], v[156:157]
	s_nop 0
	global_store_dwordx4 v[16:17], v[62:65], off offset:-1024
	v_pk_mul_f32 v[58:59], v[40:41], v[46:47] op_sel_hi:[1,0]
	v_pk_mul_f32 v[60:61], v[42:43], v[46:47] op_sel_hi:[1,0]
	v_pk_fma_f32 v[58:59], v[142:143], v[58:59], v[158:159]
	v_pk_fma_f32 v[60:61], v[144:145], v[60:61], v[160:161]
	s_nop 0
	global_store_dwordx4 v[16:17], v[58:61], off
	v_pk_mul_f32 v[62:63], v[36:37], v[46:47] op_sel_hi:[1,0]
	v_pk_mul_f32 v[64:65], v[38:39], v[46:47] op_sel_hi:[1,0]
	v_pk_fma_f32 v[62:63], v[146:147], v[62:63], v[162:163]
	v_pk_fma_f32 v[64:65], v[148:149], v[64:65], v[164:165]
	s_nop 0
	global_store_dwordx4 v[16:17], v[62:65], off offset:1024
	s_branch .LBB0_1129
